# GDN scan chunk PREP: single vmcnt wait, two merged exec-masked write regions
# speedup vs baseline: 1.0023x; 1.0017x over previous
.LBB0_245:
	s_nop 0
	v_add_u32_e32 v3, v128, v109
	v_add_u32_e32 v142, v128, v100
	ds_read_b128 v[144:147], v3 offset:592
	ds_read_b128 v[148:151], v3 offset:576
	ds_read_b128 v[152:155], v3 offset:560
	ds_read_b128 v[156:159], v3 offset:544
	ds_read_b128 v[160:163], v3
	ds_read_b128 v[164:167], v3 offset:16
	ds_read_b128 v[190:193], v3 offset:32
	ds_read_b128 v[194:197], v3 offset:48
	ds_read_b32 v143, v142 offset:1088
	ds_read_b128 v[198:201], v128 offset:1216
	v_pk_mul_f32 v[52:53], v[48:49], v[6:7]
	v_pk_mul_f32 v[34:35], v[48:49], v[34:35]
	v_pk_fma_f32 v[52:53], v[50:51], v[4:5], v[52:53]
	v_pk_fma_f32 v[32:33], v[50:51], v[32:33], v[34:35]
	v_pk_fma_f32 v[52:53], v[46:47], v[8:9], v[52:53]
	v_pk_fma_f32 v[28:29], v[46:47], v[28:29], v[32:33]
	v_pk_fma_f32 v[52:53], v[44:45], v[10:11], v[52:53]
	v_pk_fma_f32 v[28:29], v[44:45], v[30:31], v[28:29]
	v_pk_fma_f32 v[52:53], v[42:43], v[12:13], v[52:53]
	v_pk_fma_f32 v[24:25], v[42:43], v[24:25], v[28:29]
	v_pk_fma_f32 v[52:53], v[40:41], v[14:15], v[52:53]
	v_pk_fma_f32 v[24:25], v[40:41], v[26:27], v[24:25]
	v_pk_fma_f32 v[52:53], v[38:39], v[16:17], v[52:53]
	v_pk_fma_f32 v[20:21], v[38:39], v[20:21], v[24:25]
	v_pk_fma_f32 v[52:53], v[36:37], v[18:19], v[52:53]
	v_pk_fma_f32 v[20:21], v[36:37], v[22:23], v[20:21]
	v_add_f32_e32 v22, v52, v53
	v_add_f32_e32 v20, v20, v21
	v_rcp_f32_e32 v23, v0
	v_add_f32_dpp v22, v22, v22 quad_perm:[1,0,3,2] row_mask:0xf bank_mask:0xf bound_ctrl:1
	v_add_f32_dpp v20, v20, v20 quad_perm:[1,0,3,2] row_mask:0xf bank_mask:0xf bound_ctrl:1
	s_nop 0
	v_add_f32_dpp v22, v22, v22 quad_perm:[2,3,0,1] row_mask:0xf bank_mask:0xf bound_ctrl:1
	v_add_f32_dpp v20, v20, v20 quad_perm:[2,3,0,1] row_mask:0xf bank_mask:0xf bound_ctrl:1
	s_nop 0
	v_add_f32_dpp v22, v22, v22 row_half_mirror row_mask:0xf bank_mask:0xf bound_ctrl:1
	v_add_f32_dpp v20, v20, v20 row_half_mirror row_mask:0xf bank_mask:0xf bound_ctrl:1
	v_fma_f32 v21, -v0, v22, v55
	v_pk_mul_f32 v[52:53], v[0:1], v[20:21]
	s_nop 0
	v_mul_f32_e32 v20, v23, v53
	v_pk_fma_f32 v[50:51], v[4:5], v[20:21], v[50:51] op_sel_hi:[1,0,1]
	v_pk_fma_f32 v[48:49], v[6:7], v[20:21], v[48:49] op_sel_hi:[1,0,1]
	v_pk_fma_f32 v[46:47], v[8:9], v[20:21], v[46:47] op_sel_hi:[1,0,1]
	v_pk_fma_f32 v[44:45], v[10:11], v[20:21], v[44:45] op_sel_hi:[1,0,1]
	v_pk_fma_f32 v[42:43], v[12:13], v[20:21], v[42:43] op_sel_hi:[1,0,1]
	v_pk_fma_f32 v[40:41], v[14:15], v[20:21], v[40:41] op_sel_hi:[1,0,1]
	v_pk_fma_f32 v[54:55], v[16:17], v[20:21], v[38:39] op_sel_hi:[1,0,1]
	v_pk_fma_f32 v[202:203], v[18:19], v[20:21], v[36:37] op_sel_hi:[1,0,1]
	v_fmac_f32_e32 v52, v2, v53
	s_waitcnt lgkmcnt(0)
	ds_read_b128 v[4:7], v3 offset:1824
	ds_read_b128 v[8:11], v3 offset:1808
	ds_read_b128 v[12:15], v3 offset:1792
	ds_read_b128 v[16:19], v3 offset:1776
	ds_read_b128 v[20:23], v3 offset:1232
	ds_read_b128 v[24:27], v3 offset:1248
	ds_read_b128 v[28:31], v3 offset:1264
	ds_read_b128 v[32:35], v3 offset:1280
	ds_read_b32 v206, v142 offset:2320
	ds_read_b128 v[36:39], v128 offset:2448
	v_cndmask_b32_e64 v201, 0, v52, s[46:47]
	v_pk_mul_f32 v[158:159], v[48:49], v[158:159]
	v_pk_mul_f32 v[52:53], v[48:49], v[162:163]
	v_pk_fma_f32 v[156:157], v[50:51], v[156:157], v[158:159]
	v_pk_fma_f32 v[52:53], v[50:51], v[160:161], v[52:53]
	v_pk_fma_f32 v[152:153], v[46:47], v[152:153], v[156:157]
	v_pk_fma_f32 v[52:53], v[46:47], v[164:165], v[52:53]
	v_pk_fma_f32 v[152:153], v[44:45], v[154:155], v[152:153]
	v_pk_fma_f32 v[52:53], v[44:45], v[166:167], v[52:53]
	v_pk_fma_f32 v[148:149], v[42:43], v[148:149], v[152:153]
	v_pk_fma_f32 v[52:53], v[42:43], v[190:191], v[52:53]
	v_pk_fma_f32 v[148:149], v[40:41], v[150:151], v[148:149]
	v_pk_fma_f32 v[52:53], v[40:41], v[192:193], v[52:53]
	v_pk_fma_f32 v[144:145], v[54:55], v[144:145], v[148:149]
	v_pk_fma_f32 v[52:53], v[54:55], v[194:195], v[52:53]
	v_pk_fma_f32 v[144:145], v[202:203], v[146:147], v[144:145]
	v_pk_fma_f32 v[52:53], v[202:203], v[196:197], v[52:53]
	v_add_f32_e32 v2, v144, v145
	v_add_f32_e32 v1, v52, v53
	v_mul_f32_e32 v0, v0, v198
	v_add_f32_dpp v2, v2, v2 quad_perm:[1,0,3,2] row_mask:0xf bank_mask:0xf bound_ctrl:1
	v_add_f32_dpp v1, v1, v1 quad_perm:[1,0,3,2] row_mask:0xf bank_mask:0xf bound_ctrl:1
	v_mov_b32_e32 v53, v200
	v_add_f32_dpp v2, v2, v2 quad_perm:[2,3,0,1] row_mask:0xf bank_mask:0xf bound_ctrl:1
	v_add_f32_dpp v1, v1, v1 quad_perm:[2,3,0,1] row_mask:0xf bank_mask:0xf bound_ctrl:1
	s_nop 0
	v_add_f32_dpp v52, v2, v2 row_half_mirror row_mask:0xf bank_mask:0xf bound_ctrl:1
	v_rcp_f32_e32 v2, v0
	v_add_f32_dpp v1, v1, v1 row_half_mirror row_mask:0xf bank_mask:0xf bound_ctrl:1
	v_fma_f32 v1, -v0, v1, v143
	v_mul_f32_e32 v1, v199, v1
	v_mul_f32_e32 v2, v2, v1
	v_pk_fma_f32 v[198:199], v[160:161], v[2:3], v[50:51] op_sel_hi:[1,0,1]
	v_pk_fma_f32 v[204:205], v[162:163], v[2:3], v[48:49] op_sel_hi:[1,0,1]
	v_pk_fma_f32 v[164:165], v[164:165], v[2:3], v[46:47] op_sel_hi:[1,0,1]
	v_pk_fma_f32 v[166:167], v[166:167], v[2:3], v[44:45] op_sel_hi:[1,0,1]
	v_pk_fma_f32 v[190:191], v[190:191], v[2:3], v[42:43] op_sel_hi:[1,0,1]
	v_pk_fma_f32 v[192:193], v[192:193], v[2:3], v[40:41] op_sel_hi:[1,0,1]
	v_pk_fma_f32 v[194:195], v[194:195], v[2:3], v[54:55] op_sel_hi:[1,0,1]
	v_pk_fma_f32 v[196:197], v[196:197], v[2:3], v[202:203] op_sel_hi:[1,0,1]
	v_pk_mul_f32 v[40:41], v[52:53], v[0:1]
	s_waitcnt lgkmcnt(0)
	v_add_f32_e32 v1, v40, v41
	ds_read_b32 v143, v142 offset:3552
	ds_read_b128 v[40:43], v3 offset:3056
	ds_read_b128 v[44:47], v3 offset:3040
	ds_read_b128 v[48:51], v3 offset:3024
	ds_read_b128 v[52:55], v3 offset:3008
	ds_read_b128 v[144:147], v3 offset:2464
	ds_read_b128 v[148:151], v3 offset:2480
	ds_read_b128 v[152:155], v3 offset:2496
	ds_read_b128 v[156:159], v3 offset:2512
	ds_read_b128 v[160:163], v128 offset:3680
	v_cndmask_b32_e64 v2, v201, v1, s[48:49]
	v_pk_mul_f32 v[200:201], v[204:205], v[22:23]
	v_pk_mul_f32 v[18:19], v[204:205], v[18:19]
	v_pk_fma_f32 v[200:201], v[198:199], v[20:21], v[200:201]
	v_pk_fma_f32 v[16:17], v[198:199], v[16:17], v[18:19]
	v_pk_fma_f32 v[200:201], v[164:165], v[24:25], v[200:201]
	v_pk_fma_f32 v[12:13], v[164:165], v[12:13], v[16:17]
	v_pk_fma_f32 v[200:201], v[166:167], v[26:27], v[200:201]
	v_pk_fma_f32 v[12:13], v[166:167], v[14:15], v[12:13]
	v_pk_fma_f32 v[200:201], v[190:191], v[28:29], v[200:201]
	v_mul_f32_e32 v207, v0, v36
	v_pk_fma_f32 v[200:201], v[192:193], v[30:31], v[200:201]
	v_pk_fma_f32 v[8:9], v[190:191], v[8:9], v[12:13]
	v_pk_fma_f32 v[200:201], v[194:195], v[32:33], v[200:201]
	v_rcp_f32_e32 v0, v207
	v_pk_fma_f32 v[200:201], v[196:197], v[34:35], v[200:201]
	v_pk_fma_f32 v[8:9], v[192:193], v[10:11], v[8:9]
	v_add_f32_e32 v1, v200, v201
	v_pk_fma_f32 v[4:5], v[194:195], v[4:5], v[8:9]
	s_nop 0
	v_add_f32_dpp v1, v1, v1 quad_perm:[1,0,3,2] row_mask:0xf bank_mask:0xf bound_ctrl:1
	v_pk_fma_f32 v[4:5], v[196:197], v[6:7], v[4:5]
	s_nop 0
	v_add_f32_dpp v1, v1, v1 quad_perm:[2,3,0,1] row_mask:0xf bank_mask:0xf bound_ctrl:1
	v_add_f32_e32 v4, v4, v5
	s_nop 0
	v_add_f32_dpp v1, v1, v1 row_half_mirror row_mask:0xf bank_mask:0xf bound_ctrl:1
	v_fma_f32 v1, -v207, v1, v206
	v_mul_f32_e32 v206, v37, v1
	v_mul_f32_e32 v0, v0, v206
	v_add_f32_dpp v4, v4, v4 quad_perm:[1,0,3,2] row_mask:0xf bank_mask:0xf bound_ctrl:1
	v_pk_fma_f32 v[36:37], v[20:21], v[0:1], v[198:199] op_sel_hi:[1,0,1]
	v_pk_fma_f32 v[198:199], v[22:23], v[0:1], v[204:205] op_sel_hi:[1,0,1]
	v_pk_fma_f32 v[200:201], v[24:25], v[0:1], v[164:165] op_sel_hi:[1,0,1]
	v_pk_fma_f32 v[202:203], v[26:27], v[0:1], v[166:167] op_sel_hi:[1,0,1]
	v_pk_fma_f32 v[190:191], v[28:29], v[0:1], v[190:191] op_sel_hi:[1,0,1]
	v_pk_fma_f32 v[192:193], v[30:31], v[0:1], v[192:193] op_sel_hi:[1,0,1]
	v_pk_fma_f32 v[194:195], v[32:33], v[0:1], v[194:195] op_sel_hi:[1,0,1]
	v_pk_fma_f32 v[0:1], v[34:35], v[0:1], v[196:197] op_sel_hi:[1,0,1]
	v_add_f32_dpp v39, v4, v4 quad_perm:[2,3,0,1] row_mask:0xf bank_mask:0xf bound_ctrl:1
	s_waitcnt lgkmcnt(0)
	ds_read_b128 v[4:7], v3 offset:4288
	ds_read_b128 v[8:11], v3 offset:4272
	ds_read_b128 v[12:15], v3 offset:4256
	ds_read_b128 v[16:19], v3 offset:4240
	ds_read_b128 v[20:23], v3 offset:3696
	ds_read_b128 v[24:27], v3 offset:3712
	ds_read_b128 v[28:31], v3 offset:3728
	ds_read_b128 v[32:35], v3 offset:3744
	ds_read_b32 v204, v142 offset:4784
	ds_read_b128 v[164:167], v128 offset:4912
	v_add_f32_dpp v39, v39, v39 row_half_mirror row_mask:0xf bank_mask:0xf bound_ctrl:1
	v_mul_f32_e32 v38, v38, v206
	v_fmac_f32_e32 v38, v207, v39
	v_cndmask_b32_e64 v163, v2, v38, s[50:51]
	v_pk_mul_f32 v[38:39], v[198:199], v[146:147]
	v_pk_mul_f32 v[54:55], v[198:199], v[54:55]
	v_pk_fma_f32 v[38:39], v[36:37], v[144:145], v[38:39]
	v_pk_fma_f32 v[52:53], v[36:37], v[52:53], v[54:55]
	v_pk_fma_f32 v[38:39], v[200:201], v[148:149], v[38:39]
	v_pk_fma_f32 v[48:49], v[200:201], v[48:49], v[52:53]
	v_pk_fma_f32 v[38:39], v[202:203], v[150:151], v[38:39]
	v_pk_fma_f32 v[48:49], v[202:203], v[50:51], v[48:49]
	v_pk_fma_f32 v[38:39], v[190:191], v[152:153], v[38:39]
	v_pk_fma_f32 v[44:45], v[190:191], v[44:45], v[48:49]
	v_pk_fma_f32 v[38:39], v[192:193], v[154:155], v[38:39]
	v_pk_fma_f32 v[44:45], v[192:193], v[46:47], v[44:45]
	v_pk_fma_f32 v[38:39], v[194:195], v[156:157], v[38:39]
	v_pk_fma_f32 v[40:41], v[194:195], v[40:41], v[44:45]
	v_pk_fma_f32 v[38:39], v[0:1], v[158:159], v[38:39]
	v_pk_fma_f32 v[40:41], v[0:1], v[42:43], v[40:41]
	v_add_f32_e32 v2, v38, v39
	s_nop 1
	v_add_f32_dpp v2, v2, v2 quad_perm:[1,0,3,2] row_mask:0xf bank_mask:0xf bound_ctrl:1
	s_nop 1
	v_add_f32_dpp v2, v2, v2 quad_perm:[2,3,0,1] row_mask:0xf bank_mask:0xf bound_ctrl:1
	s_nop 1
	v_add_f32_dpp v38, v2, v2 row_half_mirror row_mask:0xf bank_mask:0xf bound_ctrl:1
	v_add_f32_e32 v2, v40, v41
	s_nop 1
	v_add_f32_dpp v39, v2, v2 quad_perm:[1,0,3,2] row_mask:0xf bank_mask:0xf bound_ctrl:1
	v_mul_f32_e32 v2, v207, v160
	v_rcp_f32_e32 v40, v2
	v_fma_f32 v38, -v2, v38, v143
	v_mul_f32_e32 v143, v161, v38
	v_add_f32_dpp v205, v39, v39 quad_perm:[2,3,0,1] row_mask:0xf bank_mask:0xf bound_ctrl:1
	v_mul_f32_e32 v38, v40, v143
	v_pk_fma_f32 v[36:37], v[144:145], v[38:39], v[36:37] op_sel_hi:[1,0,1]
	v_pk_fma_f32 v[40:41], v[146:147], v[38:39], v[198:199] op_sel_hi:[1,0,1]
	v_pk_fma_f32 v[42:43], v[148:149], v[38:39], v[200:201] op_sel_hi:[1,0,1]
	v_pk_fma_f32 v[44:45], v[150:151], v[38:39], v[202:203] op_sel_hi:[1,0,1]
	v_pk_fma_f32 v[46:47], v[152:153], v[38:39], v[190:191] op_sel_hi:[1,0,1]
	v_pk_fma_f32 v[48:49], v[154:155], v[38:39], v[192:193] op_sel_hi:[1,0,1]
	v_pk_fma_f32 v[50:51], v[156:157], v[38:39], v[194:195] op_sel_hi:[1,0,1]
	v_pk_fma_f32 v[0:1], v[158:159], v[38:39], v[0:1] op_sel_hi:[1,0,1]
	v_pk_mul_f32 v[160:161], v[2:3], v[36:37] op_sel_hi:[0,1]
	v_pk_mul_f32 v[190:191], v[2:3], v[40:41] op_sel_hi:[0,1]
	v_pk_mul_f32 v[192:193], v[2:3], v[42:43] op_sel_hi:[0,1]
	v_pk_mul_f32 v[194:195], v[2:3], v[44:45] op_sel_hi:[0,1]
	v_pk_mul_f32 v[196:197], v[2:3], v[46:47] op_sel_hi:[0,1]
	v_pk_mul_f32 v[198:199], v[2:3], v[48:49] op_sel_hi:[0,1]
	v_pk_mul_f32 v[200:201], v[2:3], v[50:51] op_sel_hi:[0,1]
	v_pk_mul_f32 v[0:1], v[2:3], v[0:1] op_sel_hi:[0,1]
	s_waitcnt lgkmcnt(0)
	ds_read_b128 v[36:39], v3 offset:5520
	ds_read_b128 v[40:43], v3 offset:5504
	ds_read_b128 v[44:47], v3 offset:5488
	ds_read_b128 v[48:51], v3 offset:5472
	ds_read_b128 v[52:55], v3 offset:4928
	ds_read_b128 v[144:147], v3 offset:4944
	ds_read_b128 v[148:151], v3 offset:4960
	ds_read_b128 v[152:155], v3 offset:4976
	ds_read_b32 v206, v142 offset:6016
	ds_read_b128 v[156:159], v128 offset:6144
	v_add_f32_dpp v167, v205, v205 row_half_mirror row_mask:0xf bank_mask:0xf bound_ctrl:1
	v_mul_f32_e32 v143, v162, v143
	v_fmac_f32_e32 v143, v2, v167
	v_cndmask_b32_e64 v143, v163, v143, s[52:53]
	v_pk_mul_f32 v[162:163], v[190:191], v[22:23]
	v_pk_mul_f32 v[18:19], v[190:191], v[18:19]
	v_pk_fma_f32 v[162:163], v[160:161], v[20:21], v[162:163]
	v_pk_fma_f32 v[16:17], v[160:161], v[16:17], v[18:19]
	v_pk_fma_f32 v[162:163], v[192:193], v[24:25], v[162:163]
	v_pk_fma_f32 v[12:13], v[192:193], v[12:13], v[16:17]
	v_pk_fma_f32 v[162:163], v[194:195], v[26:27], v[162:163]
	v_pk_fma_f32 v[12:13], v[194:195], v[14:15], v[12:13]
	v_pk_fma_f32 v[162:163], v[196:197], v[28:29], v[162:163]
	v_pk_fma_f32 v[8:9], v[196:197], v[8:9], v[12:13]
	v_pk_fma_f32 v[162:163], v[198:199], v[30:31], v[162:163]
	v_pk_fma_f32 v[8:9], v[198:199], v[10:11], v[8:9]
	v_pk_fma_f32 v[162:163], v[200:201], v[32:33], v[162:163]
	v_pk_fma_f32 v[4:5], v[200:201], v[4:5], v[8:9]
	v_pk_fma_f32 v[162:163], v[0:1], v[34:35], v[162:163]
	v_pk_fma_f32 v[4:5], v[0:1], v[6:7], v[4:5]
	v_add_f32_e32 v2, v162, v163
	v_add_f32_e32 v4, v4, v5
	v_rcp_f32_e32 v6, v164
	v_add_f32_dpp v2, v2, v2 quad_perm:[1,0,3,2] row_mask:0xf bank_mask:0xf bound_ctrl:1
	v_add_f32_dpp v4, v4, v4 quad_perm:[1,0,3,2] row_mask:0xf bank_mask:0xf bound_ctrl:1
	s_nop 0
	v_add_f32_dpp v2, v2, v2 quad_perm:[2,3,0,1] row_mask:0xf bank_mask:0xf bound_ctrl:1
	v_add_f32_dpp v4, v4, v4 quad_perm:[2,3,0,1] row_mask:0xf bank_mask:0xf bound_ctrl:1
	s_nop 0
	v_add_f32_dpp v2, v2, v2 row_half_mirror row_mask:0xf bank_mask:0xf bound_ctrl:1
	v_add_f32_dpp v4, v4, v4 row_half_mirror row_mask:0xf bank_mask:0xf bound_ctrl:1
	v_fma_f32 v5, -v164, v2, v204
	v_pk_mul_f32 v[202:203], v[164:165], v[4:5]
	s_nop 0
	v_mul_f32_e32 v2, v6, v203
	v_pk_fma_f32 v[204:205], v[20:21], v[2:3], v[160:161] op_sel_hi:[1,0,1]
	v_pk_fma_f32 v[190:191], v[22:23], v[2:3], v[190:191] op_sel_hi:[1,0,1]
	v_pk_fma_f32 v[192:193], v[24:25], v[2:3], v[192:193] op_sel_hi:[1,0,1]
	v_pk_fma_f32 v[194:195], v[26:27], v[2:3], v[194:195] op_sel_hi:[1,0,1]
	v_pk_fma_f32 v[196:197], v[28:29], v[2:3], v[196:197] op_sel_hi:[1,0,1]
	v_pk_fma_f32 v[198:199], v[30:31], v[2:3], v[198:199] op_sel_hi:[1,0,1]
	v_pk_fma_f32 v[200:201], v[32:33], v[2:3], v[200:201] op_sel_hi:[1,0,1]
	v_pk_fma_f32 v[0:1], v[34:35], v[2:3], v[0:1] op_sel_hi:[1,0,1]
	v_fmac_f32_e32 v202, v166, v203
	s_waitcnt lgkmcnt(0)
	ds_read_b128 v[4:7], v3 offset:6752
	ds_read_b128 v[8:11], v3 offset:6736
	ds_read_b128 v[12:15], v3 offset:6720
	ds_read_b128 v[16:19], v3 offset:6704
	ds_read_b128 v[20:23], v3 offset:6160
	ds_read_b128 v[24:27], v3 offset:6176
	ds_read_b128 v[28:31], v3 offset:6192
	ds_read_b128 v[32:35], v3 offset:6208
	ds_read_b32 v207, v142 offset:7248
	ds_read_b128 v[160:163], v128 offset:7376
	v_cndmask_b32_e64 v143, v143, v202, s[54:55]
	v_pk_mul_f32 v[166:167], v[190:191], v[54:55]
	v_pk_mul_f32 v[50:51], v[190:191], v[50:51]
	v_pk_fma_f32 v[166:167], v[204:205], v[52:53], v[166:167]
	v_pk_fma_f32 v[48:49], v[204:205], v[48:49], v[50:51]
	v_pk_fma_f32 v[166:167], v[192:193], v[144:145], v[166:167]
	v_pk_fma_f32 v[44:45], v[192:193], v[44:45], v[48:49]
	v_pk_fma_f32 v[166:167], v[194:195], v[146:147], v[166:167]
	v_pk_fma_f32 v[44:45], v[194:195], v[46:47], v[44:45]
	v_pk_fma_f32 v[166:167], v[196:197], v[148:149], v[166:167]
	v_pk_fma_f32 v[40:41], v[196:197], v[40:41], v[44:45]
	v_pk_fma_f32 v[166:167], v[198:199], v[150:151], v[166:167]
	v_mul_f32_e32 v164, v164, v156
	v_pk_fma_f32 v[166:167], v[200:201], v[152:153], v[166:167]
	v_pk_fma_f32 v[40:41], v[198:199], v[42:43], v[40:41]
	v_pk_fma_f32 v[166:167], v[0:1], v[154:155], v[166:167]
	v_pk_fma_f32 v[36:37], v[200:201], v[36:37], v[40:41]
	v_add_f32_e32 v2, v166, v167
	v_pk_fma_f32 v[36:37], v[0:1], v[38:39], v[36:37]
	s_nop 0
	v_add_f32_dpp v2, v2, v2 quad_perm:[1,0,3,2] row_mask:0xf bank_mask:0xf bound_ctrl:1
	v_add_f32_e32 v36, v36, v37
	v_mov_b32_e32 v37, v158
	v_add_f32_dpp v2, v2, v2 quad_perm:[2,3,0,1] row_mask:0xf bank_mask:0xf bound_ctrl:1
	v_add_f32_dpp v36, v36, v36 quad_perm:[1,0,3,2] row_mask:0xf bank_mask:0xf bound_ctrl:1
	s_nop 0
	v_add_f32_dpp v2, v2, v2 row_half_mirror row_mask:0xf bank_mask:0xf bound_ctrl:1
	v_fma_f32 v2, -v164, v2, v206
	v_mul_f32_e32 v165, v157, v2
	v_rcp_f32_e32 v2, v164
	v_add_f32_dpp v36, v36, v36 quad_perm:[2,3,0,1] row_mask:0xf bank_mask:0xf bound_ctrl:1
	v_mul_f32_e32 v2, v2, v165
	s_nop 0
	v_add_f32_dpp v36, v36, v36 row_half_mirror row_mask:0xf bank_mask:0xf bound_ctrl:1
	v_pk_fma_f32 v[166:167], v[52:53], v[2:3], v[204:205] op_sel_hi:[1,0,1]
	v_pk_fma_f32 v[190:191], v[54:55], v[2:3], v[190:191] op_sel_hi:[1,0,1]
	v_pk_fma_f32 v[192:193], v[144:145], v[2:3], v[192:193] op_sel_hi:[1,0,1]
	v_pk_fma_f32 v[194:195], v[146:147], v[2:3], v[194:195] op_sel_hi:[1,0,1]
	v_pk_fma_f32 v[196:197], v[148:149], v[2:3], v[196:197] op_sel_hi:[1,0,1]
	v_pk_fma_f32 v[198:199], v[150:151], v[2:3], v[198:199] op_sel_hi:[1,0,1]
	v_pk_fma_f32 v[200:201], v[152:153], v[2:3], v[200:201] op_sel_hi:[1,0,1]
	v_pk_fma_f32 v[0:1], v[154:155], v[2:3], v[0:1] op_sel_hi:[1,0,1]
	v_pk_mul_f32 v[36:37], v[36:37], v[164:165]
	s_waitcnt lgkmcnt(0)
; #define LBAR() do { asm volatile("s_waitcnt lgkmcnt(0)" ::: "memory"); __builtin_amdgcn_s_barrier(); asm volatile("" ::: "memory"); } while (0)
; #define LAS __attribute__((address_space(3)))
; #define GD_PIN(V) asm volatile("" : "+v"(V.k0), "+v"(V.k1), "+v"(V.k2), "+v"(V.k3), "+v"(V.q0), "+v"(V.q1), "+v"(V.q2), "+v"(V.q3), "+v"(V.vv), "+v"(V.abk), \
;     "+v"(S2[0]), "+v"(S2[1]), "+v"(S2[2]), "+v"(S2[3]), "+v"(S2[4]), "+v"(S2[5]), "+v"(S2[6]), "+v"(S2[7]))
; #define GD_2(jA, jB) GD_LDV(B, jA + 1); __builtin_amdgcn_sched_barrier(0); GD_STEP(A, jA); GD_PIN(B); \
;                      GD_LDV(A, jB + 1); __builtin_amdgcn_sched_barrier(0); GD_STEP(B, jB); GD_PIN(A);
; template <int NW>
; __device__ void scan_gdn(const P& p, int l, int b, int h, int dir, int part, LAS char* lds) {
;     ...
;   gd_load<TPW>(p, b, h, qc0, vc, dir, 0, wv, R);
;   GD_PREP(0);
;   gd_load<TPW>(p, b, h, qc0, vc, dir, 1, wv, R);
;   LBAR();
;   for (int g = 0; g < NCHK; ++g) {
;     LAS char* vbuf = lds + (g & 1) * TC * GD_VB;
;     LAS float* obuf = (LAS float*)(lds + GD_OFF_Y + (g & 1) * TC * NCOL * 4);
;     {
;       GdVec A, B;
;       LAS char* bk = vbuf + dq * 64 + (dq >> 2) * 16; LAS char* bv = vbuf + col * 4; LAS char* bc = vbuf;
;       GD_LDV(A, 0); GD_PIN(A);
; #pragma unroll 1
;       for (int s8 = 0; s8 < TC; s8 += 8) {
;         float ykeep = 0.f;
;         GD_2(0, 1) GD_2(2, 3) GD_2(4, 5) GD_2(6, 7)
;         obuf[(s8 + dq) * NCOL + col] = ykeep;
;         bk += 8 * GD_VB; bv += 8 * GD_VB; bc += 8 * GD_VB;
	v_add_f32_e32 v2, v36, v37
	ds_read_b32 v163, v142 offset:8480
	ds_read_b128 v[144:147], v3 offset:7984
	ds_read_b128 v[148:151], v3 offset:7968
	ds_read_b128 v[152:155], v3 offset:7952
	ds_read_b128 v[156:159], v3 offset:7936
	ds_read_b128 v[48:51], v3 offset:7392
	ds_read_b128 v[44:47], v3 offset:7408
	ds_read_b128 v[40:43], v3 offset:7424
	ds_read_b128 v[36:39], v3 offset:7440
	ds_read_b128 v[52:55], v128 offset:8608
	v_cndmask_b32_e64 v143, v143, v2, s[56:57]
	v_pk_mul_f32 v[202:203], v[190:191], v[22:23]
	v_pk_mul_f32 v[18:19], v[190:191], v[18:19]
	v_pk_fma_f32 v[202:203], v[166:167], v[20:21], v[202:203]
	v_pk_fma_f32 v[16:17], v[166:167], v[16:17], v[18:19]
	v_pk_fma_f32 v[202:203], v[192:193], v[24:25], v[202:203]
	v_pk_fma_f32 v[12:13], v[192:193], v[12:13], v[16:17]
	v_pk_fma_f32 v[202:203], v[194:195], v[26:27], v[202:203]
	v_pk_fma_f32 v[12:13], v[194:195], v[14:15], v[12:13]
	v_pk_fma_f32 v[202:203], v[196:197], v[28:29], v[202:203]
	v_pk_fma_f32 v[8:9], v[196:197], v[8:9], v[12:13]
	v_pk_fma_f32 v[202:203], v[198:199], v[30:31], v[202:203]
	v_pk_fma_f32 v[8:9], v[198:199], v[10:11], v[8:9]
	v_pk_fma_f32 v[202:203], v[200:201], v[32:33], v[202:203]
	v_pk_fma_f32 v[4:5], v[200:201], v[4:5], v[8:9]
	v_pk_fma_f32 v[202:203], v[0:1], v[34:35], v[202:203]
	v_pk_fma_f32 v[4:5], v[0:1], v[6:7], v[4:5]
	v_add_f32_e32 v2, v202, v203
	v_mul_f32_e32 v202, v164, v160
	v_add_f32_e32 v4, v4, v5
	v_add_f32_dpp v2, v2, v2 quad_perm:[1,0,3,2] row_mask:0xf bank_mask:0xf bound_ctrl:1
	v_rcp_f32_e32 v5, v202
	v_add_f32_dpp v4, v4, v4 quad_perm:[1,0,3,2] row_mask:0xf bank_mask:0xf bound_ctrl:1
	v_add_f32_dpp v2, v2, v2 quad_perm:[2,3,0,1] row_mask:0xf bank_mask:0xf bound_ctrl:1
	s_nop 0
	v_add_f32_dpp v203, v4, v4 quad_perm:[2,3,0,1] row_mask:0xf bank_mask:0xf bound_ctrl:1
	v_add_f32_dpp v2, v2, v2 row_half_mirror row_mask:0xf bank_mask:0xf bound_ctrl:1
	v_fma_f32 v2, -v202, v2, v207
	v_mul_f32_e32 v204, v161, v2
	v_mul_f32_e32 v2, v5, v204
	v_pk_fma_f32 v[160:161], v[20:21], v[2:3], v[166:167] op_sel_hi:[1,0,1]
	v_pk_fma_f32 v[164:165], v[22:23], v[2:3], v[190:191] op_sel_hi:[1,0,1]
	v_pk_fma_f32 v[166:167], v[24:25], v[2:3], v[192:193] op_sel_hi:[1,0,1]
	v_pk_fma_f32 v[190:191], v[26:27], v[2:3], v[194:195] op_sel_hi:[1,0,1]
	v_pk_fma_f32 v[192:193], v[28:29], v[2:3], v[196:197] op_sel_hi:[1,0,1]
	v_pk_fma_f32 v[194:195], v[30:31], v[2:3], v[198:199] op_sel_hi:[1,0,1]
	v_pk_fma_f32 v[196:197], v[32:33], v[2:3], v[200:201] op_sel_hi:[1,0,1]
	v_pk_fma_f32 v[198:199], v[34:35], v[2:3], v[0:1] op_sel_hi:[1,0,1]
	v_mul_f32_e32 v162, v162, v204
	s_waitcnt lgkmcnt(0)
	ds_read_b128 v[20:23], v3 offset:9216
	ds_read_b128 v[24:27], v3 offset:9200
	ds_read_b128 v[28:31], v3 offset:9184
	ds_read_b128 v[32:35], v3 offset:9168
	ds_read_b128 v[4:7], v3 offset:8624
	ds_read_b128 v[8:11], v3 offset:8640
	ds_read_b128 v[12:15], v3 offset:8656
	ds_read_b128 v[16:19], v3 offset:8672
	ds_read_b32 v55, v142 offset:9712
	ds_read_b128 v[0:3], v128 offset:9840
	v_add_f32_dpp v142, v203, v203 row_half_mirror row_mask:0xf bank_mask:0xf bound_ctrl:1
	v_fmac_f32_e32 v162, v202, v142
	v_cndmask_b32_e64 v162, v143, v162, s[58:59]
	v_pk_mul_f32 v[142:143], v[164:165], v[50:51]
	v_pk_mul_f32 v[158:159], v[164:165], v[158:159]
	v_pk_fma_f32 v[142:143], v[160:161], v[48:49], v[142:143]
	v_pk_fma_f32 v[156:157], v[160:161], v[156:157], v[158:159]
	v_pk_fma_f32 v[142:143], v[166:167], v[44:45], v[142:143]
	v_pk_fma_f32 v[152:153], v[166:167], v[152:153], v[156:157]
	v_pk_fma_f32 v[142:143], v[190:191], v[46:47], v[142:143]
	v_pk_fma_f32 v[152:153], v[190:191], v[154:155], v[152:153]
	v_pk_fma_f32 v[142:143], v[192:193], v[40:41], v[142:143]
	v_pk_fma_f32 v[148:149], v[192:193], v[148:149], v[152:153]
	v_pk_fma_f32 v[142:143], v[194:195], v[42:43], v[142:143]
	v_mul_f32_e32 v52, v202, v52
	v_pk_fma_f32 v[142:143], v[196:197], v[36:37], v[142:143]
	v_pk_fma_f32 v[148:149], v[194:195], v[150:151], v[148:149]
	v_pk_fma_f32 v[142:143], v[198:199], v[38:39], v[142:143]
	v_pk_fma_f32 v[144:145], v[196:197], v[144:145], v[148:149]
	v_add_f32_e32 v142, v142, v143
	v_pk_fma_f32 v[144:145], v[198:199], v[146:147], v[144:145]
	s_add_i32 s30, s30, 8
	v_add_f32_dpp v142, v142, v142 quad_perm:[1,0,3,2] row_mask:0xf bank_mask:0xf bound_ctrl:1
	v_add_f32_e32 v143, v144, v145
	v_add_u32_e32 v128, 0x2680, v128
	v_add_f32_dpp v142, v142, v142 quad_perm:[2,3,0,1] row_mask:0xf bank_mask:0xf bound_ctrl:1
	v_add_f32_dpp v143, v143, v143 quad_perm:[1,0,3,2] row_mask:0xf bank_mask:0xf bound_ctrl:1
	s_cmp_gt_u32 s30, 23
	v_add_f32_dpp v142, v142, v142 row_half_mirror row_mask:0xf bank_mask:0xf bound_ctrl:1
	v_fma_f32 v142, -v52, v142, v163
	v_mul_f32_e32 v53, v53, v142
	v_rcp_f32_e32 v142, v52
	v_add_f32_dpp v143, v143, v143 quad_perm:[2,3,0,1] row_mask:0xf bank_mask:0xf bound_ctrl:1
	v_mul_f32_e32 v142, v142, v53
	s_nop 0
	v_add_f32_dpp v150, v143, v143 row_half_mirror row_mask:0xf bank_mask:0xf bound_ctrl:1
	v_pk_fma_f32 v[48:49], v[48:49], v[142:143], v[160:161] op_sel_hi:[1,0,1]
	v_pk_fma_f32 v[144:145], v[50:51], v[142:143], v[164:165] op_sel_hi:[1,0,1]
	v_pk_fma_f32 v[44:45], v[44:45], v[142:143], v[166:167] op_sel_hi:[1,0,1]
	v_pk_fma_f32 v[146:147], v[46:47], v[142:143], v[190:191] op_sel_hi:[1,0,1]
	v_pk_fma_f32 v[40:41], v[40:41], v[142:143], v[192:193] op_sel_hi:[1,0,1]
	v_pk_fma_f32 v[148:149], v[42:43], v[142:143], v[194:195] op_sel_hi:[1,0,1]
	v_pk_fma_f32 v[36:37], v[36:37], v[142:143], v[196:197] op_sel_hi:[1,0,1]
	v_pk_fma_f32 v[142:143], v[38:39], v[142:143], v[198:199] op_sel_hi:[1,0,1]
	v_mul_f32_e32 v38, v54, v53
	v_fmac_f32_e32 v38, v52, v150
	v_cndmask_b32_e64 v53, v162, v38, s[60:61]
	v_pk_mul_f32 v[50:51], v[52:53], v[48:49] op_sel_hi:[0,1]
	v_pk_mul_f32 v[48:49], v[52:53], v[144:145] op_sel_hi:[0,1]
	v_pk_mul_f32 v[46:47], v[52:53], v[44:45] op_sel_hi:[0,1]
	v_pk_mul_f32 v[44:45], v[52:53], v[146:147] op_sel_hi:[0,1]
	v_pk_mul_f32 v[42:43], v[52:53], v[40:41] op_sel_hi:[0,1]
	v_pk_mul_f32 v[40:41], v[52:53], v[148:149] op_sel_hi:[0,1]
	v_pk_mul_f32 v[38:39], v[52:53], v[36:37] op_sel_hi:[0,1]
	v_pk_mul_f32 v[36:37], v[52:53], v[142:143] op_sel_hi:[0,1]
	s_waitcnt lgkmcnt(0)
	s_nop 0
	v_add_u32_e32 v3, v141, v100
	v_add_u32_e32 v141, 0x400, v141
	ds_write_b32 v3, v53
	s_cbranch_scc0 .LBB0_245
	s_add_i32 s30, s26, 1
	s_cmpk_lg_i32 s26, 0x87
	s_cbranch_scc0 .LBB0_280
	s_lshl_b32 s20, s30, 5
	s_and_b32 s20, s20, 32
	s_mulk_i32 s20, 0x4d0
	s_waitcnt vmcnt(0)
	v_lshlrev_b32_e32 v3, 16, v81
	v_lshlrev_b32_e32 v4, 16, v82
	v_add_u32_e32 v0, s20, v78
	v_lshlrev_b32_e32 v1, 16, v79
	v_lshlrev_b32_e32 v2, 16, v80
	ds_write2_b32 v0, v3, v4 offset1:68
	ds_write2_b32 v0, v1, v2 offset0:136 offset1:204
	v_lshlrev_b32_e32 v3, 16, v87
	v_lshlrev_b32_e32 v4, 16, v88
	v_add_u32_e32 v5, 0x400, v0
	v_lshlrev_b32_e32 v1, 16, v85
	v_lshlrev_b32_e32 v2, 16, v86
	ds_write2_b32 v5, v3, v4 offset0:52 offset1:120
	v_add_u32_e32 v3, 0x600, v0
	ds_write2_b32 v3, v1, v2 offset0:60 offset1:128
	v_lshlrev_b32_e32 v3, 16, v93
	v_lshlrev_b32_e32 v4, 16, v94
	v_add_u32_e32 v5, 0x800, v0
	v_lshlrev_b32_e32 v1, 16, v91
	v_lshlrev_b32_e32 v2, 16, v92
	ds_write2_b32 v5, v3, v4 offset0:104 offset1:172
	v_add_u32_e32 v3, 0xa00, v0
	ds_write2_b32 v3, v1, v2 offset0:112 offset1:180
	v_lshlrev_b32_e32 v3, 16, v107
	v_lshlrev_b32_e32 v4, 16, v108
	v_add_u32_e32 v5, 0xc00, v0
	v_lshlrev_b32_e32 v1, 16, v103
	v_lshlrev_b32_e32 v2, 16, v105
	ds_write2_b32 v5, v3, v4 offset0:156 offset1:224
	v_add_u32_e32 v3, 0x1000, v0
	ds_write2_b32 v3, v1, v2 offset0:36 offset1:104
	v_lshlrev_b32_e32 v3, 16, v115
	v_lshlrev_b32_e32 v4, 16, v116
	v_add_u32_e32 v5, 0x1200, v0
	v_lshlrev_b32_e32 v1, 16, v113
	v_lshlrev_b32_e32 v2, 16, v114
	ds_write2_b32 v5, v3, v4 offset0:80 offset1:148
	v_add_u32_e32 v3, 0x1400, v0
	ds_write2_b32 v3, v1, v2 offset0:88 offset1:156
	v_lshlrev_b32_e32 v3, 16, v121
	v_lshlrev_b32_e32 v4, 16, v122
	v_add_u32_e32 v5, 0x1800, v0
	v_lshlrev_b32_e32 v1, 16, v119
	v_lshlrev_b32_e32 v2, 16, v120
	ds_write2_b32 v5, v3, v4 offset0:4 offset1:72
	ds_write2_b32 v5, v1, v2 offset0:140 offset1:208
	v_lshlrev_b32_e32 v3, 16, v127
	v_lshlrev_b32_e32 v4, 16, v134
	v_add_u32_e32 v5, 0x1c00, v0
	v_lshlrev_b32_e32 v1, 16, v125
	v_lshlrev_b32_e32 v2, 16, v126
	ds_write2_b32 v5, v3, v4 offset0:56 offset1:124
	v_add_u32_e32 v3, 0x1e00, v0
	ds_write2_b32 v3, v1, v2 offset0:64 offset1:132
	v_lshlrev_b32_e32 v3, 16, v138
	v_lshlrev_b32_e32 v4, 16, v139
	v_add_u32_e32 v5, 0x2000, v0
	v_lshlrev_b32_e32 v1, 16, v57
	v_lshlrev_b32_e32 v2, 16, v137
	ds_write2_b32 v5, v3, v4 offset0:108 offset1:176
	v_add_u32_e32 v3, 0x2200, v0
	ds_write2_b32 v3, v1, v2 offset0:116 offset1:184
	s_and_saveexec_b64 s[36:37], s[38:39]
	v_lshlrev_b32_e32 v1, 16, v83
	ds_write_b32 v0, v1 offset:1088
	v_lshlrev_b32_e32 v1, 16, v89
	ds_write_b32 v0, v1 offset:2320
	v_lshlrev_b32_e32 v1, 16, v95
	ds_write_b32 v0, v1 offset:3552
	v_lshlrev_b32_e32 v1, 16, v111
	ds_write_b32 v0, v1 offset:4784
	v_lshlrev_b32_e32 v1, 16, v117
	ds_write_b32 v0, v1 offset:6016
	v_lshlrev_b32_e32 v1, 16, v123
	ds_write_b32 v0, v1 offset:7248
	v_lshlrev_b32_e32 v1, 16, v135
	ds_write_b32 v0, v1 offset:8480
	v_lshlrev_b32_e32 v1, 16, v59
	ds_write_b32 v0, v1 offset:9712
	s_or_b64 exec, exec, s[36:37]
	s_and_saveexec_b64 s[36:37], s[40:41]
	v_cndmask_b32_e64 v1, v84, v61, s[44:45]
	v_cndmask_b32_e64 v1, v1, v60, s[42:43]
	ds_write_b32 v0, v1 offset:1216
	v_cndmask_b32_e64 v1, v90, v63, s[44:45]
	v_cndmask_b32_e64 v1, v1, v62, s[42:43]
	ds_write_b32 v0, v1 offset:2448
	v_cndmask_b32_e64 v1, v96, v65, s[44:45]
	v_cndmask_b32_e64 v1, v1, v64, s[42:43]
	ds_write_b32 v0, v1 offset:3680
	v_cndmask_b32_e64 v1, v112, v67, s[44:45]
	v_cndmask_b32_e64 v1, v1, v66, s[42:43]
	ds_write_b32 v0, v1 offset:4912
	v_cndmask_b32_e64 v1, v118, v69, s[44:45]
	v_cndmask_b32_e64 v1, v1, v68, s[42:43]
	ds_write_b32 v0, v1 offset:6144
	v_cndmask_b32_e64 v1, v124, v71, s[44:45]
	v_cndmask_b32_e64 v1, v1, v70, s[42:43]
	ds_write_b32 v0, v1 offset:7376
	v_cndmask_b32_e64 v1, v136, v73, s[44:45]
	v_cndmask_b32_e64 v1, v1, v72, s[42:43]
	ds_write_b32 v0, v1 offset:8608
	v_cndmask_b32_e64 v1, v140, v75, s[44:45]
	v_cndmask_b32_e64 v1, v1, v74, s[42:43]
	ds_write_b32 v0, v1 offset:9840
	s_or_b64 exec, exec, s[36:37]
